# diff-attention block A: row-max chain and cross-half bpermute issued before the QK MFMA chain (bpermute latency hidden behind QK)
# speedup vs baseline: 1.0044x; 1.0003x over previous
.LstgV_skip:
	v_mfma_f32_32x32x16_bf16 v[48:63], v[160:163], v[144:147], v[48:63]
	ds_read_b64_tr_b16 v[180:181], v238 offset:8192
	ds_read_b64_tr_b16 v[182:183], v238 offset:8704
	v_exp_f32_e32 v249, v88
	v_exp_f32_e32 v250, v89
	v_add_f32_e32 v100, v247, v100
	v_add_f32_e32 v101, v248, v101
	v_mfma_f32_32x32x16_bf16 v[48:63], v[164:167], v[148:151], v[48:63]
	ds_read_b64_tr_b16 v[176:177], v238 offset:9216
	ds_read_b64_tr_b16 v[178:179], v238 offset:9728
	ds_read_b128 v[128:131], v96 offset:4096
	v_exp_f32_e32 v251, v90
	v_exp_f32_e32 v252, v91
	v_add_f32_e32 v100, v249, v100
	v_add_f32_e32 v101, v250, v101
	v_mfma_f32_32x32x16_bf16 v[16:31], v[160:163], v[152:155], v[16:31]
	ds_read_b64_tr_b16 v[172:173], v238 offset:12288
	ds_read_b64_tr_b16 v[174:175], v238 offset:12800
	v_exp_f32_e32 v253, v92
	v_exp_f32_e32 v239, v93
	v_add_f32_e32 v100, v251, v100
	v_add_f32_e32 v101, v252, v101
	v_mfma_f32_32x32x16_bf16 v[16:31], v[164:167], v[156:159], v[16:31]
	ds_read_b64_tr_b16 v[168:169], v238 offset:13312
	ds_read_b64_tr_b16 v[170:171], v238 offset:13824
	ds_read_b128 v[132:135], v97 offset:4096
	ds_read_b128 v[136:139], v98 offset:4096
	ds_read_b128 v[140:143], v99 offset:4096
	v_exp_f32_e32 v240, v94
	v_exp_f32_e32 v99, v95
	v_add_f32_e32 v100, v253, v100
	v_add_f32_e32 v101, v239, v101
	v_add_f32_e32 v100, v240, v100
	v_add_f32_e32 v101, v99, v101
	v_add_f32_e32 v100, v100, v101
	v_add_f32_e32 v235, v235, v100
	v_cvt_pk_bf16_f32 v156, v241, v242
	v_cvt_pk_bf16_f32 v157, v243, v244
	v_cvt_pk_bf16_f32 v158, v245, v246
	v_cvt_pk_bf16_f32 v159, v247, v248
	v_cvt_pk_bf16_f32 v162, v249, v250
	v_cvt_pk_bf16_f32 v163, v251, v252
	v_cvt_pk_bf16_f32 v164, v253, v239
	v_cvt_pk_bf16_f32 v165, v240, v99
	v_max3_f32 v144, v80, v81, v82
	v_max3_f32 v145, v83, v84, v85
	v_max3_f32 v144, v144, v86, v87
	v_max3_f32 v145, v145, v88, v89
	v_max3_f32 v144, v144, v90, v91
	v_max3_f32 v145, v145, v92, v93
	v_max3_f32 v144, v144, v94, v95
	v_max_f32_e32 v144, v144, v145
	ds_bpermute_b32 v145, v214, v144
	s_waitcnt lgkmcnt(8)
	v_mfma_f32_32x32x16_bf16 v[96:111], v[128:131], v[112:115], v[64:79]
	s_waitcnt lgkmcnt(3)
	v_mfma_f32_32x32x16_bf16 v[96:111], v[132:135], v[116:119], v[96:111]
	s_waitcnt lgkmcnt(2)
	v_mfma_f32_32x32x16_bf16 v[96:111], v[136:139], v[120:123], v[96:111]
	s_waitcnt lgkmcnt(1)
	v_mfma_f32_32x32x16_bf16 v[96:111], v[140:143], v[124:127], v[96:111]
	s_andn2_b64 vcc, exec, s[0:1]
	s_cbranch_vccz .LBB0_522
.LBB0_510:
	s_waitcnt lgkmcnt(0)
	v_max_f32_e32 v80, v144, v145
	v_cmp_lt_f32_e32 vcc, s67, v80
	s_cmp_lg_u64 vcc, 0
	s_cselect_b64 s[0:1], -1, 0
	s_cbranch_vccnz .LBB0_525

.LBB0_522:
	s_and_saveexec_b64 s[0:1], s[4:5]
	ds_write_b32 v236, v232
	s_or_b64 exec, exec, s[0:1]
	s_waitcnt lgkmcnt(0)
	ds_read_b128 v[130:133], v237 offset:96
	ds_read_b128 v[134:137], v237 offset:64
	ds_read_b128 v[138:141], v237 offset:32
	ds_read_b128 v[146:149], v237
	s_waitcnt lgkmcnt(0)
	s_waitcnt lgkmcnt(3)
	v_pk_mul_f32 v[14:15], v[14:15], v[132:133]
	s_waitcnt lgkmcnt(2)
	v_pk_mul_f32 v[10:11], v[10:11], v[136:137]
	s_waitcnt lgkmcnt(1)
	v_pk_mul_f32 v[6:7], v[6:7], v[140:141]
	s_waitcnt lgkmcnt(0)
	v_pk_mul_f32 v[2:3], v[2:3], v[148:149]
	v_pk_mul_f32 v[12:13], v[12:13], v[130:131]
	v_pk_mul_f32 v[8:9], v[8:9], v[134:135]
	v_pk_mul_f32 v[4:5], v[4:5], v[138:139]
	v_pk_mul_f32 v[0:1], v[0:1], v[146:147]
	v_pk_mul_f32 v[46:47], v[46:47], v[132:133]
	v_pk_mul_f32 v[42:43], v[42:43], v[136:137]
	v_pk_mul_f32 v[38:39], v[38:39], v[140:141]
	v_pk_mul_f32 v[34:35], v[34:35], v[148:149]
	v_pk_mul_f32 v[44:45], v[44:45], v[130:131]
	v_pk_mul_f32 v[40:41], v[40:41], v[134:135]
	v_pk_mul_f32 v[36:37], v[36:37], v[138:139]
	v_pk_mul_f32 v[32:33], v[32:33], v[146:147]
	v_pk_mul_f32 v[62:63], v[62:63], v[132:133]
	v_pk_mul_f32 v[58:59], v[58:59], v[136:137]
	v_pk_mul_f32 v[54:55], v[54:55], v[140:141]
	v_pk_mul_f32 v[50:51], v[50:51], v[148:149]
	v_pk_mul_f32 v[60:61], v[60:61], v[130:131]
	v_pk_mul_f32 v[56:57], v[56:57], v[134:135]
	v_pk_mul_f32 v[52:53], v[52:53], v[138:139]
	v_pk_mul_f32 v[48:49], v[48:49], v[146:147]
	v_pk_mul_f32 v[30:31], v[30:31], v[132:133]
	v_pk_mul_f32 v[26:27], v[26:27], v[136:137]
	v_pk_mul_f32 v[22:23], v[22:23], v[140:141]
	v_pk_mul_f32 v[18:19], v[18:19], v[148:149]
	v_pk_mul_f32 v[28:29], v[28:29], v[130:131]
	v_pk_mul_f32 v[24:25], v[24:25], v[134:135]
	v_pk_mul_f32 v[20:21], v[20:21], v[138:139]
	v_pk_mul_f32 v[16:17], v[16:17], v[146:147]
	s_branch .LBB0_510
